# XCD-local grid barriers, conservative set (20 of 36): own-batch hand-offs with no workspace pitch change in the window skip L2 write-back + cross-XCD rendezvous
# speedup vs baseline: 1.0139x; 1.0110x over previous
; #define LAS __attribute__((address_space(3)))
; __device__ __forceinline__ unsigned xb_ld(unsigned* p)              { return __hip_atomic_load(p, __ATOMIC_RELAXED, __HIP_MEMORY_SCOPE_AGENT); }
; __device__ __forceinline__ unsigned xb_add(unsigned* p, unsigned v) { return __hip_atomic_fetch_add(p, v, __ATOMIC_RELAXED, __HIP_MEMORY_SCOPE_AGENT); }
; __device__ __forceinline__ void xcd_barrier(const XcdBarrier& b) {
;     asm volatile("s_waitcnt vmcnt(0)" ::: "memory");
;     __syncthreads();
;     if (threadIdx.x == 0) {
;         unsigned* bar = b.bar;
;         __builtin_amdgcn_s_waitcnt(0);
;         unsigned nloc = b.st[0], nx = b.st[1];
;         if (nloc == 0u) { xcd_barrier_complete(bar, b.x, nloc, nx); b.st[0] = nloc; b.st[1] = nx; }
;         const unsigned old = xb_add(&bar[XB_XSUB(b.x)], 1u);
;         const unsigned gen = old / nloc;
;         if (old + 1u == (gen + 1u) * nloc) {
;             __builtin_amdgcn_fence(__ATOMIC_RELEASE, "agent");
;             asm volatile("s_waitcnt vmcnt(0)" ::: "memory");
;             const unsigned og = xb_add(&bar[XB_TOP], 1u);
;             const unsigned tg = og / nx;
;             if (og + 1u == (tg + 1u) * nx) xb_add(&bar[XB_TOPGEN], 1u);
;             else XB_SPIN(xb_ld(&bar[XB_TOPGEN]) == tg, bar);
;             __builtin_amdgcn_fence(__ATOMIC_ACQUIRE, "agent");
;             xb_add(&bar[XB_XGEN(b.x)], 1u);
; __global__ void __launch_bounds__(NTHREADS) mega_kernel(Params p_) {
;     ...
;         if (coop && ph + 1 < ph_hi) {
;             if (ph == 0) {
;                 cg::this_grid().sync();
;                 volatile LAS unsigned* st_ = (volatile LAS unsigned*)(F.lds + 131072 + 64);
;                 if (threadIdx.x == 0) {
;                     unsigned* bar_ = (unsigned*)F.ws; bool ok_ = (gridDim.x % 8u) == 0u;
;                     for (unsigned j = 0; j < 16; ++j) { const unsigned c_ = xb_ld(&bar_[XB_XCNT(j)]); ok_ = ok_ && (c_ == (j < 8u ? gridDim.x / 8u : 0u)); }
;                     const unsigned x_ = xb_xcc_id();
;                     st_[3] = (ok_ && x_ < 8u && st_[2] < gridDim.x / 8u) ? (st_[2] * 8u + x_) : blockIdx.x;
;                 }
;                 __syncthreads();
;             }
;             else { XcdBarrier xb_; xb_.bar = (unsigned*)F.ws; xb_.x = xb_xcc_id(); xb_.st = (volatile LAS unsigned*)(F.lds + 131072 + 64); xcd_barrier(xb_); if (SYNC2) xcd_barrier(xb_); }
.LBB0_790:
	s_andn2_saveexec_b64 s[8:9], s[8:9]
	s_cbranch_execz .LBB0_1139
	v_readlane_b32 s8, v255, 62
	v_readlane_b32 s9, v254, 24
	v_readlane_b32 s10, v254, 27
	s_cmp_eq_u32 s8, 0
	s_cbranch_scc1 .Lxb_global
	s_lshr_b32 s8, 0x6c8, s9
	s_bitcmp1_b32 s8, 0
	s_cbranch_scc1 .Lxb_local
	s_cmp_lg_u32 s9, 1
	s_cbranch_scc1 .Lxb_global
	s_cmp_lg_u32 s10, 0
	s_cbranch_scc1 .Lxb_local
.Lxb_global:
	s_mov_b64 s[8:9], exec
	buffer_wbl2 sc1
	s_waitcnt lgkmcnt(0)
	s_waitcnt vmcnt(0)
	v_mbcnt_lo_u32_b32 v1, s8, 0
	v_mbcnt_hi_u32_b32 v1, s9, v1
	v_cmp_eq_u32_e32 vcc, 0, v1
	s_and_saveexec_b64 s[10:11], vcc
	s_cbranch_execz .LBB0_793
	s_bcnt1_i32_b64 s8, s[8:9]
	v_mov_b32_e32 v2, s8
	v_mov_b32_e32 v3, 0x3000
	global_atomic_add v2, v3, v2, s[90:91] offset:1024 sc0

; __device__ __forceinline__ unsigned xb_add(unsigned* p, unsigned v) { return __hip_atomic_fetch_add(p, v, __ATOMIC_RELAXED, __HIP_MEMORY_SCOPE_AGENT); }
; __device__ __forceinline__ void xcd_barrier(const XcdBarrier& b) {
;     ...
;             __builtin_amdgcn_fence(__ATOMIC_ACQUIRE, "agent");
;             xb_add(&bar[XB_XGEN(b.x)], 1u);
.Lxb_local:
	s_mov_b64 s[8:9], exec
	v_mbcnt_lo_u32_b32 v0, s8, 0
	v_mbcnt_hi_u32_b32 v0, s9, v0
	v_cmp_eq_u32_e32 vcc, 0, v0
	s_waitcnt vmcnt(0)
	buffer_inv sc1
	s_and_saveexec_b64 s[10:11], vcc
	s_cbranch_execz .LBB0_1138
	s_bcnt1_i32_b64 s8, s[8:9]
	v_mov_b32_e32 v0, s8
	v_mov_b32_e32 v1, 0x2000
	global_atomic_add v1, v0, s[6:7] offset:1024

; #define LAS __attribute__((address_space(3)))
; __device__ __forceinline__ unsigned xb_ld(unsigned* p)              { return __hip_atomic_load(p, __ATOMIC_RELAXED, __HIP_MEMORY_SCOPE_AGENT); }
; __device__ __forceinline__ unsigned xb_xcc_id() { return (unsigned)__builtin_amdgcn_s_getreg((3 << 11) | 20) & 0xFu; }
; __global__ void __launch_bounds__(NTHREADS) mega_kernel(Params p_) {
;     ...
;             if (ph == 0) {
;                 cg::this_grid().sync();
;                 volatile LAS unsigned* st_ = (volatile LAS unsigned*)(F.lds + 131072 + 64);
;                 if (threadIdx.x == 0) {
;                     unsigned* bar_ = (unsigned*)F.ws; bool ok_ = (gridDim.x % 8u) == 0u;
;                     for (unsigned j = 0; j < 16; ++j) { const unsigned c_ = xb_ld(&bar_[XB_XCNT(j)]); ok_ = ok_ && (c_ == (j < 8u ? gridDim.x / 8u : 0u)); }
;                     const unsigned x_ = xb_xcc_id();
;                     st_[3] = (ok_ && x_ < 8u && st_[2] < gridDim.x / 8u) ? (st_[2] * 8u + x_) : blockIdx.x;
;                 }
.LBB0_1151:
	v_writelane_b32 v255, 0, 62
	global_load_dword v0, v165, s[90:91] offset:1024 sc1
	s_lshr_b32 s8, s82, 3
	v_readlane_b32 s6, v254, 20
	v_readlane_b32 s7, v254, 21
	s_waitcnt vmcnt(0)
	v_cmp_eq_u32_e32 vcc, s8, v0
	global_load_dword v0, v165, s[90:91] offset:1280 sc1
	s_and_b64 s[6:7], s[6:7], vcc
	s_waitcnt vmcnt(0)
	v_cmp_eq_u32_e32 vcc, s8, v0
	global_load_dword v0, v165, s[90:91] offset:1536 sc1
	s_and_b64 s[6:7], s[6:7], vcc
	s_waitcnt vmcnt(0)
	v_cmp_eq_u32_e32 vcc, s8, v0
	global_load_dword v0, v165, s[90:91] offset:1792 sc1
	s_and_b64 s[6:7], s[6:7], vcc
	s_waitcnt vmcnt(0)
	v_cmp_eq_u32_e32 vcc, s8, v0
	global_load_dword v0, v165, s[90:91] offset:2048 sc1
	s_and_b64 s[6:7], s[6:7], vcc
	s_waitcnt vmcnt(0)
	v_cmp_eq_u32_e32 vcc, s8, v0
	global_load_dword v0, v165, s[90:91] offset:2304 sc1
	s_and_b64 s[6:7], s[6:7], vcc
	s_waitcnt vmcnt(0)
	v_cmp_eq_u32_e32 vcc, s8, v0
	global_load_dword v0, v165, s[90:91] offset:2560 sc1
	s_and_b64 s[6:7], s[6:7], vcc
	s_waitcnt vmcnt(0)
	v_cmp_eq_u32_e32 vcc, s8, v0
	global_load_dword v0, v165, s[90:91] offset:2816 sc1
	s_and_b64 s[6:7], s[6:7], vcc
	s_waitcnt vmcnt(0)
	v_cmp_eq_u32_e32 vcc, s8, v0
	global_load_dword v0, v165, s[90:91] offset:3072 sc1
	s_and_b64 s[6:7], s[6:7], vcc
	s_waitcnt vmcnt(0)
	v_cmp_eq_u32_e32 vcc, 0, v0
	global_load_dword v0, v165, s[90:91] offset:3328 sc1
	s_and_b64 s[6:7], s[6:7], vcc
	s_waitcnt vmcnt(0)
	v_cmp_eq_u32_e32 vcc, 0, v0
	global_load_dword v0, v165, s[90:91] offset:3584 sc1
	s_and_b64 s[6:7], s[6:7], vcc
	s_waitcnt vmcnt(0)
	v_cmp_eq_u32_e32 vcc, 0, v0
	global_load_dword v0, v165, s[90:91] offset:3840 sc1
	s_and_b64 s[6:7], s[6:7], vcc
	s_waitcnt vmcnt(0)
	v_cmp_eq_u32_e32 vcc, 0, v0
	global_load_dword v0, v215, s[90:91] sc1
	s_and_b64 s[6:7], s[6:7], vcc
	s_waitcnt vmcnt(0)
	v_cmp_eq_u32_e32 vcc, 0, v0
	global_load_dword v0, v215, s[90:91] offset:256 sc1
	s_and_b64 s[6:7], s[6:7], vcc
	s_waitcnt vmcnt(0)
	v_cmp_eq_u32_e32 vcc, 0, v0
	global_load_dword v0, v215, s[90:91] offset:512 sc1
	s_and_b64 s[6:7], s[6:7], vcc
	s_waitcnt vmcnt(0)
	v_cmp_eq_u32_e32 vcc, 0, v0
	global_load_dword v0, v215, s[90:91] offset:768 sc1
	s_and_b64 s[6:7], s[6:7], vcc
	s_getreg_b32 s9, hwreg(HW_REG_XCC_ID, 0, 4)
	s_and_b32 s9, s9, 15
	s_waitcnt vmcnt(0)
	v_cmp_eq_u32_e32 vcc, 0, v0
	s_and_b64 s[6:7], s[6:7], vcc
	s_cmp_lt_u32 s9, 8
	s_cselect_b64 s[10:11], -1, 0
	s_and_b64 s[6:7], s[6:7], s[10:11]
	s_andn2_b64 vcc, exec, s[6:7]
	v_readlane_b32 s6, v254, 0
	s_nop 1
	v_mov_b32_e32 v0, s6
	s_cbranch_vccz .LBB0_1152
	s_getpc_b64 s[98:99]

; __device__ __forceinline__ unsigned xb_xcc_id() { return (unsigned)__builtin_amdgcn_s_getreg((3 << 11) | 20) & 0xFu; }
; __global__ void __launch_bounds__(NTHREADS) mega_kernel(Params p_) {
;     ...
;                     const unsigned x_ = xb_xcc_id();
;                     st_[3] = (ok_ && x_ < 8u && st_[2] < gridDim.x / 8u) ? (st_[2] * 8u + x_) : blockIdx.x;
.LBB0_1153:
	v_writelane_b32 v255, 1, 62
	v_readlane_b32 s6, v254, 14
	s_nop 1
	v_mov_b32_e32 v0, s6
	ds_read_b32 v0, v0
	s_waitcnt lgkmcnt(0)
	v_lshlrev_b32_e32 v0, 3, v0
	v_or_b32_e32 v0, s9, v0
	s_getpc_b64 s[98:99]
